# EpiUp act-store tail: bpermute transpose pipelined one store group ahead (counted lgkmcnt(4))
# baseline (speedup 1.0000x reference)
.LBB0_408:
	s_or_b64 exec, exec, s[38:39]
	s_mov_b32 s4, 0x358637bd
	v_pk_add_f32 v[240:241], v[240:241], v[242:243]
	v_mov_b64_e32 v[214:215], s[4:5]
	v_pk_fma_f32 v[240:241], v[240:241], s[90:91], v[214:215] op_sel_hi:[1,0,0]
	v_pk_add_f32 v[236:237], v[236:237], v[238:239]
	v_mul_f32_e32 v216, 0x4b800000, v240
	v_cmp_gt_f32_e64 s[42:43], s10, v240
	v_cmp_gt_f32_e32 vcc, s10, v241
	v_pk_fma_f32 v[214:215], v[236:237], s[90:91], v[214:215] op_sel_hi:[1,0,0]
	v_cndmask_b32_e64 v216, v240, v216, s[42:43]
	v_rsq_f32_e32 v216, v216
	s_mov_b64 s[26:27], -1
	v_mul_f32_e32 v217, 0x45800000, v216
	v_cndmask_b32_e64 v240, v216, v217, s[42:43]
	v_mul_f32_e32 v216, 0x4b800000, v241
	v_cndmask_b32_e32 v216, v241, v216, vcc
	v_rsq_f32_e32 v216, v216
	v_cmp_gt_f32_e64 s[42:43], s10, v214
	v_pk_mul_f32 v[16:17], v[16:17], v[240:241] op_sel_hi:[1,0]
	v_mul_f32_e32 v217, 0x45800000, v216
	v_cndmask_b32_e32 v242, v216, v217, vcc
	v_mul_f32_e32 v216, 0x4b800000, v214
	v_cndmask_b32_e64 v214, v214, v216, s[42:43]
	v_rsq_f32_e32 v214, v214
	v_cmp_gt_f32_e32 vcc, s10, v215
	v_pk_mul_f32 v[220:221], v[68:69], v[242:243] op_sel_hi:[1,0]
	v_pk_mul_f32 v[218:219], v[66:67], v[242:243] op_sel_hi:[1,0]
	v_mul_f32_e32 v216, 0x45800000, v214
	v_cndmask_b32_e64 v236, v214, v216, s[42:43]
	v_mul_f32_e32 v214, 0x4b800000, v215
	v_cndmask_b32_e32 v214, v215, v214, vcc
	v_rsq_f32_e32 v214, v214
	v_pk_mul_f32 v[216:217], v[72:73], v[240:241] op_sel_hi:[1,0]
	v_pk_mul_f32 v[72:73], v[64:65], v[236:237] op_sel_hi:[1,0]
	s_waitcnt vmcnt(3)
	v_pk_mul_f32 v[64:65], v[154:155], v[198:199]
	v_mul_f32_e32 v215, 0x45800000, v214
	v_cndmask_b32_e32 v238, v214, v215, vcc
	v_pk_mul_f32 v[68:69], v[60:61], v[238:239] op_sel_hi:[1,0]
	v_pk_mul_f32 v[60:61], v[178:179], v[198:199]
	v_pk_mul_f32 v[66:67], v[58:59], v[238:239] op_sel_hi:[1,0]
	v_pk_mul_f32 v[58:59], v[180:181], v[200:201]
	v_pk_fma_f32 v[60:61], v[154:155], v[194:195], v[60:61]
	v_pk_mul_f32 v[214:215], v[70:71], v[240:241] op_sel_hi:[1,0]
	v_pk_mul_f32 v[70:71], v[62:63], v[236:237] op_sel_hi:[1,0]
	v_pk_fma_f32 v[58:59], v[156:157], v[196:197], v[58:59]
	v_pk_fma_f32 v[60:61], v[66:67], v[190:191], v[60:61]
	v_pk_mul_f32 v[62:63], v[156:157], v[200:201]
	v_pk_fma_f32 v[64:65], v[66:67], v[194:195], v[64:65]
	v_pk_mul_f32 v[66:67], v[66:67], v[198:199]
	v_pk_fma_f32 v[58:59], v[68:69], v[192:193], v[58:59]
	v_pk_fma_f32 v[62:63], v[68:69], v[196:197], v[62:63]
	v_pk_fma_f32 v[64:65], v[70:71], v[190:191], v[64:65]
	v_pk_mul_f32 v[68:69], v[68:69], v[200:201]
	v_pk_fma_f32 v[154:155], v[70:71], v[194:195], v[66:67]
	v_pk_mul_f32 v[70:71], v[70:71], v[198:199]
	v_pk_fma_f32 v[62:63], v[72:73], v[192:193], v[62:63]
	v_pk_fma_f32 v[66:67], v[72:73], v[196:197], v[68:69]
	v_pk_fma_f32 v[68:69], v[218:219], v[190:191], v[154:155]
	v_pk_mul_f32 v[72:73], v[72:73], v[200:201]
	v_pk_fma_f32 v[154:155], v[218:219], v[194:195], v[70:71]
	v_pk_fma_f32 v[70:71], v[220:221], v[196:197], v[72:73]
	v_pk_fma_f32 v[72:73], v[214:215], v[190:191], v[154:155]
	v_pk_mul_f32 v[154:155], v[220:221], v[200:201]
	v_pk_mul_f32 v[156:157], v[218:219], v[198:199]
	v_pk_fma_f32 v[154:155], v[216:217], v[196:197], v[154:155]
	v_pk_fma_f32 v[156:157], v[214:215], v[194:195], v[156:157]
	v_pk_mul_f32 v[178:179], v[216:217], v[200:201]
	v_pk_mul_f32 v[180:181], v[214:215], v[198:199]
	v_pk_fma_f32 v[154:155], v[128:129], v[192:193], v[154:155]
	v_pk_fma_f32 v[156:157], v[126:127], v[190:191], v[156:157]
	v_pk_fma_f32 v[180:181], v[126:127], v[194:195], v[180:181]
	v_pk_fma_f32 v[178:179], v[128:129], v[196:197], v[178:179]
	v_pk_mul_f32 v[128:129], v[128:129], v[200:201]
	v_pk_mul_f32 v[126:127], v[126:127], v[198:199]
	v_pk_fma_f32 v[128:129], v[124:125], v[196:197], v[128:129]
	v_pk_fma_f32 v[214:215], v[122:123], v[194:195], v[126:127]
	s_waitcnt lgkmcnt(0)
	v_pk_mul_f32 v[196:197], v[196:197], v[204:205]
	v_pk_mul_f32 v[194:195], v[194:195], v[202:203]
	v_pk_fma_f32 v[178:179], v[124:125], v[192:193], v[178:179]
	v_pk_fma_f32 v[124:125], v[124:125], v[200:201], v[196:197]
	v_pk_fma_f32 v[194:195], v[122:123], v[198:199], v[194:195]
	v_pk_mul_f32 v[198:199], v[38:39], v[236:237] op_sel_hi:[1,0]
	v_pk_mul_f32 v[200:201], v[40:41], v[236:237] op_sel_hi:[1,0]
	v_pk_mul_f32 v[38:39], v[144:145], v[176:177]
	v_pk_mul_f32 v[40:41], v[142:143], v[174:175]
	v_pk_mul_f32 v[34:35], v[34:35], v[238:239] op_sel_hi:[1,0]
	v_pk_mul_f32 v[36:37], v[36:37], v[238:239] op_sel_hi:[1,0]
	v_pk_fma_f32 v[38:39], v[136:137], v[164:165], v[38:39]
	v_pk_fma_f32 v[40:41], v[134:135], v[162:163], v[40:41]
	v_pk_fma_f32 v[66:67], v[220:221], v[192:193], v[66:67]
	v_pk_fma_f32 v[70:71], v[216:217], v[192:193], v[70:71]
	v_pk_fma_f32 v[180:181], v[122:123], v[190:191], v[180:181]
	v_pk_fma_f32 v[126:127], v[192:193], v[204:205], v[128:129]
	v_pk_fma_f32 v[128:129], v[190:191], v[202:203], v[214:215]
	v_pk_fma_f32 v[122:123], v[192:193], v[208:209], v[124:125]
	v_pk_fma_f32 v[124:125], v[190:191], v[206:207], v[194:195]
	v_pk_mul_f32 v[190:191], v[54:55], v[240:241] op_sel_hi:[1,0]
	v_pk_mul_f32 v[192:193], v[56:57], v[240:241] op_sel_hi:[1,0]
	v_pk_fma_f32 v[56:57], v[36:37], v[160:161], v[38:39]
	v_pk_fma_f32 v[54:55], v[34:35], v[158:159], v[40:41]
	v_pk_mul_f32 v[38:39], v[136:137], v[176:177]
	v_pk_mul_f32 v[40:41], v[134:135], v[174:175]
	v_pk_fma_f32 v[38:39], v[36:37], v[164:165], v[38:39]
	v_pk_fma_f32 v[40:41], v[34:35], v[162:163], v[40:41]
	v_pk_mul_f32 v[36:37], v[36:37], v[176:177]
	v_pk_mul_f32 v[34:35], v[34:35], v[174:175]
	v_pk_mul_f32 v[194:195], v[50:51], v[242:243] op_sel_hi:[1,0]
	v_pk_mul_f32 v[196:197], v[52:53], v[242:243] op_sel_hi:[1,0]
	v_pk_fma_f32 v[34:35], v[198:199], v[162:163], v[34:35]
	v_pk_fma_f32 v[36:37], v[200:201], v[164:165], v[36:37]
	v_pk_fma_f32 v[52:53], v[200:201], v[160:161], v[38:39]
	v_pk_fma_f32 v[50:51], v[198:199], v[158:159], v[40:41]
	v_pk_fma_f32 v[40:41], v[196:197], v[160:161], v[36:37]
	v_pk_fma_f32 v[38:39], v[194:195], v[158:159], v[34:35]
	v_pk_mul_f32 v[34:35], v[200:201], v[176:177]
	v_pk_mul_f32 v[36:37], v[198:199], v[174:175]
	v_pk_fma_f32 v[34:35], v[196:197], v[164:165], v[34:35]
	v_pk_fma_f32 v[134:135], v[194:195], v[162:163], v[36:37]
	v_pk_mul_f32 v[136:137], v[194:195], v[174:175]
	v_pk_fma_f32 v[36:37], v[192:193], v[160:161], v[34:35]
	v_pk_fma_f32 v[34:35], v[190:191], v[158:159], v[134:135]
	v_pk_mul_f32 v[134:135], v[196:197], v[176:177]
	v_pk_fma_f32 v[136:137], v[190:191], v[162:163], v[136:137]
	v_pk_mul_f32 v[144:145], v[190:191], v[174:175]
	v_pk_fma_f32 v[134:135], v[192:193], v[164:165], v[134:135]
	v_pk_fma_f32 v[136:137], v[118:119], v[158:159], v[136:137]
	v_pk_mul_f32 v[142:143], v[192:193], v[176:177]
	v_pk_fma_f32 v[144:145], v[118:119], v[162:163], v[144:145]
	v_pk_mul_f32 v[118:119], v[118:119], v[174:175]
	v_pk_fma_f32 v[134:135], v[120:121], v[160:161], v[134:135]
	v_pk_fma_f32 v[142:143], v[120:121], v[164:165], v[142:143]
	v_pk_mul_f32 v[120:121], v[120:121], v[176:177]
	v_pk_fma_f32 v[118:119], v[114:115], v[162:163], v[118:119]
	v_pk_fma_f32 v[120:121], v[116:117], v[164:165], v[120:121]
	v_pk_fma_f32 v[192:193], v[158:159], v[182:183], v[118:119]
	v_pk_mul_f32 v[118:119], v[164:165], v[184:185]
	v_pk_mul_f32 v[164:165], v[30:31], v[240:241] op_sel_hi:[1,0]
	v_pk_mul_f32 v[30:31], v[132:133], v[152:153]
	v_pk_fma_f32 v[142:143], v[116:117], v[160:161], v[142:143]
	v_pk_fma_f32 v[116:117], v[116:117], v[176:177], v[118:119]
	v_pk_mul_f32 v[20:21], v[20:21], v[238:239] op_sel_hi:[1,0]
	v_pk_fma_f32 v[30:31], v[104:105], v[148:149], v[30:31]
	v_pk_fma_f32 v[190:191], v[160:161], v[184:185], v[120:121]
	v_pk_fma_f32 v[160:161], v[160:161], v[188:189], v[116:117]
	v_pk_fma_f32 v[116:117], v[20:21], v[140:141], v[30:31]
	v_pk_mul_f32 v[30:31], v[104:105], v[152:153]
	v_pk_mul_f32 v[120:121], v[162:163], v[182:183]
	v_pk_mul_f32 v[162:163], v[32:33], v[240:241] op_sel_hi:[1,0]
	v_pk_mul_f32 v[24:25], v[24:25], v[236:237] op_sel_hi:[1,0]
	v_pk_mul_f32 v[32:33], v[130:131], v[150:151]
	v_pk_fma_f32 v[30:31], v[20:21], v[148:149], v[30:31]
	v_pk_mul_f32 v[20:21], v[20:21], v[152:153]
	v_pk_fma_f32 v[144:145], v[114:115], v[158:159], v[144:145]
	v_pk_fma_f32 v[114:115], v[114:115], v[174:175], v[120:121]
	v_pk_mul_f32 v[28:29], v[28:29], v[242:243] op_sel_hi:[1,0]
	v_pk_mul_f32 v[18:19], v[18:19], v[238:239] op_sel_hi:[1,0]
	v_pk_fma_f32 v[32:33], v[102:103], v[146:147], v[32:33]
	v_pk_fma_f32 v[20:21], v[24:25], v[148:149], v[20:21]
	v_pk_fma_f32 v[158:159], v[158:159], v[186:187], v[114:115]
	v_pk_fma_f32 v[114:115], v[18:19], v[138:139], v[32:33]
	v_pk_mul_f32 v[32:33], v[102:103], v[150:151]
	v_pk_fma_f32 v[120:121], v[28:29], v[140:141], v[20:21]
	v_pk_mul_f32 v[20:21], v[24:25], v[152:153]
	v_pk_mul_f32 v[22:23], v[22:23], v[236:237] op_sel_hi:[1,0]
	v_pk_fma_f32 v[32:33], v[18:19], v[146:147], v[32:33]
	v_pk_mul_f32 v[18:19], v[18:19], v[150:151]
	v_pk_fma_f32 v[20:21], v[28:29], v[148:149], v[20:21]
	v_pk_mul_f32 v[26:27], v[26:27], v[242:243] op_sel_hi:[1,0]
	v_pk_fma_f32 v[18:19], v[22:23], v[146:147], v[18:19]
	v_pk_fma_f32 v[132:133], v[162:163], v[140:141], v[20:21]
	v_pk_mul_f32 v[20:21], v[28:29], v[152:153]
	v_pk_fma_f32 v[118:119], v[26:27], v[138:139], v[18:19]
	v_pk_mul_f32 v[18:19], v[22:23], v[150:151]
	v_pk_fma_f32 v[20:21], v[162:163], v[148:149], v[20:21]
	v_pk_fma_f32 v[102:103], v[22:23], v[138:139], v[32:33]
	v_pk_fma_f32 v[18:19], v[26:27], v[146:147], v[18:19]
	v_pk_fma_f32 v[32:33], v[112:113], v[140:141], v[20:21]
	v_pk_mul_f32 v[20:21], v[162:163], v[152:153]
	v_pk_fma_f32 v[130:131], v[164:165], v[138:139], v[18:19]
	v_pk_mul_f32 v[18:19], v[26:27], v[150:151]
	v_pk_fma_f32 v[20:21], v[112:113], v[148:149], v[20:21]
	v_pk_fma_f32 v[18:19], v[164:165], v[146:147], v[18:19]
	v_pk_fma_f32 v[28:29], v[108:109], v[140:141], v[20:21]
	v_pk_mul_f32 v[20:21], v[110:111], v[150:151]
	v_pk_fma_f32 v[104:105], v[24:25], v[140:141], v[30:31]
	v_pk_fma_f32 v[30:31], v[110:111], v[138:139], v[18:19]
	v_pk_mul_f32 v[18:19], v[164:165], v[150:151]
	v_pk_fma_f32 v[20:21], v[106:107], v[146:147], v[20:21]
	v_pk_fma_f32 v[18:19], v[110:111], v[146:147], v[18:19]
	v_pk_fma_f32 v[24:25], v[138:139], v[166:167], v[20:21]
	v_pk_mul_f32 v[20:21], v[146:147], v[166:167]
	v_pk_fma_f32 v[26:27], v[106:107], v[138:139], v[18:19]
	v_pk_fma_f32 v[20:21], v[106:107], v[150:151], v[20:21]
	v_mul_f32_e32 v106, 0xbfb8aa3b, v158
	v_mul_f32_e32 v107, 0xbfb8aa3b, v159
	v_exp_f32_e32 v106, v106
	v_exp_f32_e32 v107, v107
	v_pk_mul_f32 v[18:19], v[112:113], v[152:153]
	v_pk_fma_f32 v[20:21], v[138:139], v[170:171], v[20:21]
	v_pk_fma_f32 v[18:19], v[108:109], v[148:149], v[18:19]
	v_add_f32_e32 v106, 1.0, v106
	v_add_f32_e32 v107, 1.0, v107
	v_pk_fma_f32 v[22:23], v[140:141], v[168:169], v[18:19]
	v_pk_mul_f32 v[18:19], v[148:149], v[168:169]
	v_rcp_f32_e32 v106, v106
	v_rcp_f32_e32 v107, v107
	v_pk_fma_f32 v[18:19], v[108:109], v[152:153], v[18:19]
	v_pk_mul_f32 v[26:27], v[144:145], v[26:27]
	v_pk_fma_f32 v[18:19], v[140:141], v[172:173], v[18:19]
	v_pk_mul_f32 v[28:29], v[142:143], v[28:29]
	v_pk_mul_f32 v[108:109], v[160:161], v[18:19]
	v_pk_mul_f32 v[18:19], v[158:159], v[20:21]
	v_mul_f32_e32 v20, 0xbfb8aa3b, v160
	v_mul_f32_e32 v21, 0xbfb8aa3b, v161
	v_pk_mul_f32 v[18:19], v[106:107], v[18:19]
	v_exp_f32_e32 v20, v20
	v_exp_f32_e32 v21, v21
	v_mul_f32_e32 v106, 0xbfb8aa3b, v192
	v_mul_f32_e32 v107, 0xbfb8aa3b, v193
	v_exp_f32_e32 v106, v106
	v_exp_f32_e32 v107, v107
	v_add_f32_e32 v20, 1.0, v20
	v_add_f32_e32 v21, 1.0, v21
	v_rcp_f32_e32 v20, v20
	v_rcp_f32_e32 v21, v21
	v_add_f32_e32 v106, 1.0, v106
	v_add_f32_e32 v107, 1.0, v107
	v_rcp_f32_e32 v106, v106
	v_rcp_f32_e32 v107, v107
	v_pk_mul_f32 v[20:21], v[20:21], v[108:109]
	v_pk_mul_f32 v[108:109], v[190:191], v[22:23]
	v_pk_mul_f32 v[22:23], v[192:193], v[24:25]
	v_pk_mul_f32 v[30:31], v[136:137], v[30:31]
	v_pk_mul_f32 v[22:23], v[106:107], v[22:23]
	v_mul_f32_e32 v106, 0xbfb8aa3b, v144
	v_mul_f32_e32 v107, 0xbfb8aa3b, v145
	v_exp_f32_e32 v106, v106
	v_exp_f32_e32 v107, v107
	v_mul_f32_e32 v24, 0xbfb8aa3b, v190
	v_mul_f32_e32 v25, 0xbfb8aa3b, v191
	v_add_f32_e32 v106, 1.0, v106
	v_add_f32_e32 v107, 1.0, v107
	v_rcp_f32_e32 v106, v106
	v_rcp_f32_e32 v107, v107
	v_pk_mul_f32 v[32:33], v[134:135], v[32:33]
	v_exp_f32_e32 v24, v24
	v_exp_f32_e32 v25, v25
	v_pk_mul_f32 v[26:27], v[106:107], v[26:27]
	v_mul_f32_e32 v106, 0xbfb8aa3b, v142
	v_mul_f32_e32 v107, 0xbfb8aa3b, v143
	v_exp_f32_e32 v106, v106
	v_exp_f32_e32 v107, v107
	v_add_f32_e32 v24, 1.0, v24
	v_add_f32_e32 v25, 1.0, v25
	v_add_f32_e32 v106, 1.0, v106
	v_add_f32_e32 v107, 1.0, v107
	v_rcp_f32_e32 v106, v106
	v_rcp_f32_e32 v107, v107
	v_rcp_f32_e32 v24, v24
	v_rcp_f32_e32 v25, v25
	v_pk_mul_f32 v[104:105], v[52:53], v[104:105]
	v_pk_mul_f32 v[28:29], v[106:107], v[28:29]
	v_mul_f32_e32 v106, 0xbfb8aa3b, v136
	v_mul_f32_e32 v107, 0xbfb8aa3b, v137
	v_exp_f32_e32 v106, v106
	v_exp_f32_e32 v107, v107
	v_pk_mul_f32 v[24:25], v[24:25], v[108:109]
	v_pk_mul_f32 v[108:109], v[36:37], v[132:133]
	v_add_f32_e32 v106, 1.0, v106
	v_add_f32_e32 v107, 1.0, v107
	v_rcp_f32_e32 v106, v106
	v_rcp_f32_e32 v107, v107
	v_mul_f32_e32 v36, 0xbfb8aa3b, v36
	v_mul_f32_e32 v37, 0xbfb8aa3b, v37
	v_exp_f32_e32 v36, v36
	v_pk_mul_f32 v[30:31], v[106:107], v[30:31]
	v_mul_f32_e32 v106, 0xbfb8aa3b, v134
	v_mul_f32_e32 v107, 0xbfb8aa3b, v135
	v_exp_f32_e32 v106, v106
	v_exp_f32_e32 v107, v107
	v_exp_f32_e32 v37, v37
	v_mul_f32_e32 v52, 0xbfb8aa3b, v52
	v_add_f32_e32 v106, 1.0, v106
	v_add_f32_e32 v107, 1.0, v107
	v_rcp_f32_e32 v106, v106
	v_rcp_f32_e32 v107, v107
	v_mul_f32_e32 v53, 0xbfb8aa3b, v53
	v_exp_f32_e32 v52, v52
	v_exp_f32_e32 v53, v53
	v_pk_mul_f32 v[32:33], v[106:107], v[32:33]
	v_mul_f32_e32 v106, 0xbfb8aa3b, v34
	v_mul_f32_e32 v107, 0xbfb8aa3b, v35
	v_exp_f32_e32 v106, v106
	v_exp_f32_e32 v107, v107
	v_pk_mul_f32 v[34:35], v[34:35], v[130:131]
	v_add_f32_e32 v36, 1.0, v36
	v_add_f32_e32 v106, 1.0, v106
	v_add_f32_e32 v107, 1.0, v107
	v_rcp_f32_e32 v106, v106
	v_rcp_f32_e32 v107, v107
	v_add_f32_e32 v37, 1.0, v37
	v_rcp_f32_e32 v36, v36
	v_rcp_f32_e32 v37, v37
	v_pk_mul_f32 v[34:35], v[106:107], v[34:35]
	v_mul_f32_e32 v106, 0xbfb8aa3b, v38
	v_mul_f32_e32 v107, 0xbfb8aa3b, v39
	v_exp_f32_e32 v106, v106
	v_exp_f32_e32 v107, v107
	v_add_f32_e32 v52, 1.0, v52
	v_add_f32_e32 v53, 1.0, v53
	v_add_f32_e32 v106, 1.0, v106
	v_add_f32_e32 v107, 1.0, v107
	v_rcp_f32_e32 v106, v106
	v_rcp_f32_e32 v107, v107
	v_rcp_f32_e32 v52, v52
	v_rcp_f32_e32 v53, v53
	v_pk_mul_f32 v[36:37], v[36:37], v[108:109]
	v_pk_mul_f32 v[108:109], v[40:41], v[120:121]
	v_pk_mul_f32 v[38:39], v[38:39], v[118:119]
	v_mul_f32_e32 v40, 0xbfb8aa3b, v40
	v_mul_f32_e32 v41, 0xbfb8aa3b, v41
	v_pk_mul_f32 v[38:39], v[106:107], v[38:39]
	v_exp_f32_e32 v40, v40
	v_exp_f32_e32 v41, v41
	v_mul_f32_e32 v106, 0xbfb8aa3b, v50
	v_mul_f32_e32 v107, 0xbfb8aa3b, v51
	v_pk_mul_f32 v[50:51], v[50:51], v[102:103]
	v_pk_mul_f32 v[52:53], v[52:53], v[104:105]
	v_mul_f32_e32 v102, 0xbfb8aa3b, v54
	v_mul_f32_e32 v103, 0xbfb8aa3b, v55
	v_pk_mul_f32 v[104:105], v[56:57], v[116:117]
	v_mul_f32_e32 v56, 0xbfb8aa3b, v56
	v_mul_f32_e32 v57, 0xbfb8aa3b, v57
	v_exp_f32_e32 v102, v102
	v_exp_f32_e32 v103, v103
	v_exp_f32_e32 v56, v56
	v_exp_f32_e32 v57, v57
	v_exp_f32_e32 v106, v106
	v_exp_f32_e32 v107, v107
	v_add_f32_e32 v40, 1.0, v40
	v_add_f32_e32 v41, 1.0, v41
	v_rcp_f32_e32 v40, v40
	v_rcp_f32_e32 v41, v41
	v_add_f32_e32 v102, 1.0, v102
	v_add_f32_e32 v103, 1.0, v103
	v_add_f32_e32 v56, 1.0, v56
	v_add_f32_e32 v57, 1.0, v57
	v_rcp_f32_e32 v102, v102
	v_rcp_f32_e32 v103, v103
	v_rcp_f32_e32 v56, v56
	v_rcp_f32_e32 v57, v57
	v_add_f32_e32 v106, 1.0, v106
	v_add_f32_e32 v107, 1.0, v107
	v_rcp_f32_e32 v106, v106
	v_rcp_f32_e32 v107, v107
	v_pk_mul_f32 v[40:41], v[40:41], v[108:109]
	v_pk_mul_f32 v[54:55], v[54:55], v[114:115]
	v_pk_mul_f32 v[108:109], v[2:3], v[238:239] op_sel_hi:[1,0]
	s_waitcnt vmcnt(0)
	v_pk_mul_f32 v[2:3], v[76:77], v[92:93]
	v_pk_mul_f32 v[54:55], v[102:103], v[54:55]
	v_pk_mul_f32 v[56:57], v[56:57], v[104:105]
	v_pk_mul_f32 v[102:103], v[10:11], v[242:243] op_sel_hi:[1,0]
	v_pk_mul_f32 v[104:105], v[4:5], v[238:239] op_sel_hi:[1,0]
	v_pk_mul_f32 v[4:5], v[74:75], v[90:91]
	v_pk_fma_f32 v[10:11], v[84:85], v[88:89], v[2:3]
	v_pk_fma_f32 v[2:3], v[82:83], v[86:87], v[4:5]
	v_pk_fma_f32 v[4:5], v[104:105], v[80:81], v[10:11]
	v_pk_mul_f32 v[10:11], v[84:85], v[92:93]
	v_pk_mul_f32 v[50:51], v[106:107], v[50:51]
	v_pk_mul_f32 v[106:107], v[14:15], v[240:241] op_sel_hi:[1,0]
	v_pk_mul_f32 v[8:9], v[8:9], v[236:237] op_sel_hi:[1,0]
	v_pk_mul_f32 v[14:15], v[82:83], v[90:91]
	v_pk_fma_f32 v[74:75], v[104:105], v[88:89], v[10:11]
	v_pk_mul_f32 v[76:77], v[104:105], v[92:93]
	v_pk_mul_f32 v[12:13], v[12:13], v[242:243] op_sel_hi:[1,0]
	v_pk_fma_f32 v[10:11], v[108:109], v[86:87], v[14:15]
	v_pk_fma_f32 v[14:15], v[8:9], v[80:81], v[74:75]
	v_pk_fma_f32 v[76:77], v[8:9], v[88:89], v[76:77]
	v_pk_mul_f32 v[8:9], v[8:9], v[92:93]
	v_pk_mul_f32 v[6:7], v[6:7], v[236:237] op_sel_hi:[1,0]
	v_pk_fma_f32 v[8:9], v[12:13], v[88:89], v[8:9]
	v_pk_mul_f32 v[74:75], v[108:109], v[90:91]
	v_pk_fma_f32 v[84:85], v[16:17], v[80:81], v[8:9]
	v_pk_mul_f32 v[8:9], v[12:13], v[92:93]
	v_pk_fma_f32 v[10:11], v[6:7], v[78:79], v[10:11]
	v_pk_fma_f32 v[74:75], v[6:7], v[86:87], v[74:75]
	v_pk_mul_f32 v[6:7], v[6:7], v[90:91]
	v_pk_fma_f32 v[8:9], v[16:17], v[88:89], v[8:9]
	v_pk_fma_f32 v[6:7], v[102:103], v[86:87], v[6:7]
	v_pk_fma_f32 v[104:105], v[48:49], v[80:81], v[8:9]
	v_pk_mul_f32 v[8:9], v[16:17], v[92:93]
	v_pk_fma_f32 v[82:83], v[106:107], v[78:79], v[6:7]
	v_pk_mul_f32 v[6:7], v[102:103], v[90:91]
	v_pk_fma_f32 v[8:9], v[48:49], v[88:89], v[8:9]
	v_pk_fma_f32 v[2:3], v[108:109], v[78:79], v[2:3]
	v_pk_fma_f32 v[6:7], v[106:107], v[86:87], v[6:7]
	v_pk_fma_f32 v[108:109], v[44:45], v[80:81], v[8:9]
	v_pk_mul_f32 v[8:9], v[46:47], v[90:91]
	v_pk_fma_f32 v[74:75], v[102:103], v[78:79], v[74:75]
	v_pk_fma_f32 v[102:103], v[46:47], v[78:79], v[6:7]
	v_pk_mul_f32 v[6:7], v[106:107], v[90:91]
	v_pk_fma_f32 v[8:9], v[42:43], v[86:87], v[8:9]
	v_pk_fma_f32 v[6:7], v[46:47], v[86:87], v[6:7]
	v_pk_fma_f32 v[16:17], v[78:79], v[94:95], v[8:9]
	v_pk_mul_f32 v[8:9], v[86:87], v[94:95]
	v_pk_fma_f32 v[106:107], v[42:43], v[78:79], v[6:7]
	v_pk_fma_f32 v[8:9], v[42:43], v[90:91], v[8:9]
	v_mul_f32_e32 v42, 0xbfb8aa3b, v124
	v_mul_f32_e32 v43, 0xbfb8aa3b, v125
	v_exp_f32_e32 v42, v42
	v_exp_f32_e32 v43, v43
	v_pk_mul_f32 v[6:7], v[48:49], v[92:93]
	v_pk_fma_f32 v[76:77], v[12:13], v[80:81], v[76:77]
	v_pk_fma_f32 v[6:7], v[44:45], v[88:89], v[6:7]
	v_add_f32_e32 v42, 1.0, v42
	v_add_f32_e32 v43, 1.0, v43
	v_pk_fma_f32 v[12:13], v[80:81], v[96:97], v[6:7]
	v_pk_mul_f32 v[6:7], v[88:89], v[96:97]
	v_rcp_f32_e32 v42, v42
	v_rcp_f32_e32 v43, v43
	v_pk_fma_f32 v[6:7], v[44:45], v[92:93], v[6:7]
	v_pk_fma_f32 v[8:9], v[78:79], v[98:99], v[8:9]
	v_pk_fma_f32 v[6:7], v[80:81], v[100:101], v[6:7]
	v_pk_mul_f32 v[46:47], v[180:181], v[106:107]
	v_pk_mul_f32 v[44:45], v[122:123], v[6:7]
	v_pk_mul_f32 v[6:7], v[124:125], v[8:9]
	v_mul_f32_e32 v8, 0xbfb8aa3b, v122
	v_mul_f32_e32 v9, 0xbfb8aa3b, v123
	v_pk_mul_f32 v[6:7], v[42:43], v[6:7]
	v_exp_f32_e32 v8, v8
	v_exp_f32_e32 v9, v9
	v_mul_f32_e32 v42, 0xbfb8aa3b, v128
	v_mul_f32_e32 v43, 0xbfb8aa3b, v129
	v_exp_f32_e32 v42, v42
	v_exp_f32_e32 v43, v43
	v_add_f32_e32 v8, 1.0, v8
	v_add_f32_e32 v9, 1.0, v9
	v_rcp_f32_e32 v8, v8
	v_rcp_f32_e32 v9, v9
	v_add_f32_e32 v42, 1.0, v42
	v_add_f32_e32 v43, 1.0, v43
	v_rcp_f32_e32 v42, v42
	v_rcp_f32_e32 v43, v43
	v_pk_mul_f32 v[8:9], v[8:9], v[44:45]
	v_pk_mul_f32 v[44:45], v[126:127], v[12:13]
	v_pk_mul_f32 v[12:13], v[128:129], v[16:17]
	v_mul_f32_e32 v16, 0xbfb8aa3b, v126
	v_pk_mul_f32 v[12:13], v[42:43], v[12:13]
	v_mul_f32_e32 v42, 0xbfb8aa3b, v180
	v_mul_f32_e32 v43, 0xbfb8aa3b, v181
	v_exp_f32_e32 v42, v42
	v_exp_f32_e32 v43, v43
	v_mul_f32_e32 v17, 0xbfb8aa3b, v127
	v_exp_f32_e32 v16, v16
	v_add_f32_e32 v42, 1.0, v42
	v_add_f32_e32 v43, 1.0, v43
	v_rcp_f32_e32 v42, v42
	v_rcp_f32_e32 v43, v43
	v_exp_f32_e32 v17, v17
	v_add_f32_e32 v16, 1.0, v16
	v_pk_mul_f32 v[14:15], v[62:63], v[14:15]
	v_pk_mul_f32 v[42:43], v[42:43], v[46:47]
	v_mul_f32_e32 v46, 0xbfb8aa3b, v178
	v_mul_f32_e32 v47, 0xbfb8aa3b, v179
	v_exp_f32_e32 v46, v46
	v_exp_f32_e32 v47, v47
	v_add_f32_e32 v17, 1.0, v17
	v_mul_f32_e32 v62, 0xbfb8aa3b, v62
	v_mul_f32_e32 v63, 0xbfb8aa3b, v63
	v_rcp_f32_e32 v16, v16
	v_rcp_f32_e32 v17, v17
	v_add_f32_e32 v46, 1.0, v46
	v_add_f32_e32 v47, 1.0, v47
	v_exp_f32_e32 v62, v62
	v_exp_f32_e32 v63, v63
	v_rcp_f32_e32 v46, v46
	v_rcp_f32_e32 v47, v47
	v_pk_mul_f32 v[16:17], v[16:17], v[44:45]
	v_pk_mul_f32 v[44:45], v[178:179], v[108:109]
	v_add_f32_e32 v62, 1.0, v62
	v_add_f32_e32 v63, 1.0, v63
	v_pk_mul_f32 v[44:45], v[46:47], v[44:45]
	v_mul_f32_e32 v46, 0xbfb8aa3b, v156
	v_mul_f32_e32 v47, 0xbfb8aa3b, v157
	v_rcp_f32_e32 v62, v62
	v_rcp_f32_e32 v63, v63
	v_exp_f32_e32 v46, v46
	v_exp_f32_e32 v47, v47
	v_pk_mul_f32 v[78:79], v[156:157], v[102:103]
	v_pk_mul_f32 v[14:15], v[62:63], v[14:15]
	v_mul_f32_e32 v62, 0xbfb8aa3b, v60
	v_mul_f32_e32 v63, 0xbfb8aa3b, v61
	v_add_f32_e32 v46, 1.0, v46
	v_add_f32_e32 v47, 1.0, v47
	v_exp_f32_e32 v62, v62
	v_exp_f32_e32 v63, v63
	v_rcp_f32_e32 v46, v46
	v_rcp_f32_e32 v47, v47
	v_add_f32_e32 v62, 1.0, v62
	v_add_f32_e32 v63, 1.0, v63
	v_rcp_f32_e32 v62, v62
	v_pk_mul_f32 v[46:47], v[46:47], v[78:79]
	v_mul_f32_e32 v78, 0xbfb8aa3b, v154
	v_mul_f32_e32 v79, 0xbfb8aa3b, v155
	v_rcp_f32_e32 v63, v63
	v_exp_f32_e32 v78, v78
	v_exp_f32_e32 v79, v79
	v_pk_mul_f32 v[2:3], v[60:61], v[2:3]
	v_pk_mul_f32 v[48:49], v[154:155], v[104:105]
	v_pk_mul_f32 v[60:61], v[62:63], v[2:3]
	v_mul_f32_e32 v2, 0xbfb8aa3b, v58
	v_mul_f32_e32 v3, 0xbfb8aa3b, v59
	v_add_f32_e32 v78, 1.0, v78
	v_add_f32_e32 v79, 1.0, v79
	v_exp_f32_e32 v2, v2
	v_exp_f32_e32 v3, v3
	v_rcp_f32_e32 v78, v78
	v_rcp_f32_e32 v79, v79
	v_add_f32_e32 v2, 1.0, v2
	v_add_f32_e32 v3, 1.0, v3
	v_rcp_f32_e32 v2, v2
	v_pk_mul_f32 v[48:49], v[78:79], v[48:49]
	v_mul_f32_e32 v78, 0xbfb8aa3b, v72
	v_mul_f32_e32 v79, 0xbfb8aa3b, v73
	v_rcp_f32_e32 v3, v3
	v_exp_f32_e32 v78, v78
	v_exp_f32_e32 v79, v79
	v_pk_mul_f32 v[4:5], v[58:59], v[4:5]
	v_pk_mul_f32 v[80:81], v[70:71], v[84:85]
	v_pk_mul_f32 v[58:59], v[2:3], v[4:5]
	v_cvt_pk_bf16_f32 v4, v6, v7
	v_lshrrev_b32_e32 v130, 2, v213
	v_and_b32_e32 v131, 3, v213
	v_lshlrev_b32_e32 v134, 6, v131
	v_lshl_add_u32 v134, v130, 2, v134
	v_sub_u32_e32 v135, v130, v249
	v_lshl_add_u32 v135, v135, 3, v232
	v_sub_u32_e32 v136, v131, v250
	v_lshl_add_u32 v132, v136, 3, v234
	v_mov_b32_e32 v133, v235
	v_lshlrev_b64 v[132:133], 1, v[132:133]
	v_mov_b64_e32 v[6:7], s[46:47]
	v_add_f32_e32 v78, 1.0, v78
	v_add_f32_e32 v79, 1.0, v79
	v_cvt_pk_bf16_f32 v2, v18, v19
	v_cvt_pk_bf16_f32 v5, v8, v9
	v_mad_i64_i32 v[8:9], s[4:5], v135, s92, v[6:7]
	v_lshlrev_b64 v[18:19], 1, v[234:235]
	v_rcp_f32_e32 v78, v78
	v_rcp_f32_e32 v79, v79
	v_cvt_pk_bf16_f32 v3, v20, v21
	v_lshl_add_u64 v[8:9], v[8:9], 0, v[132:133]
	v_mul_f32_e32 v70, 0xbfb8aa3b, v70
	v_mul_f32_e32 v71, 0xbfb8aa3b, v71
	ds_bpermute_b32 v138, v134, v2
	ds_bpermute_b32 v139, v134, v3
	ds_bpermute_b32 v140, v134, v4
	ds_bpermute_b32 v141, v134, v5
	v_mov_b64_e32 v[146:147], v[8:9]
	v_or_b32_e32 v8, 1, v135
	v_exp_f32_e32 v70, v70
	v_exp_f32_e32 v71, v71
	v_mad_i64_i32 v[8:9], s[4:5], v8, s92, v[6:7]
	v_pk_mul_f32 v[72:73], v[72:73], v[82:83]
	v_cvt_pk_bf16_f32 v2, v22, v23
	v_cvt_pk_bf16_f32 v3, v24, v25
	v_cvt_pk_bf16_f32 v4, v12, v13
	v_cvt_pk_bf16_f32 v5, v16, v17
	v_lshl_add_u64 v[8:9], v[8:9], 0, v[132:133]
	v_pk_mul_f32 v[72:73], v[78:79], v[72:73]
	v_mul_f32_e32 v78, 0xbfb8aa3b, v68
	v_mul_f32_e32 v79, 0xbfb8aa3b, v69
	v_pk_mul_f32 v[76:77], v[66:67], v[76:77]
	v_mul_f32_e32 v66, 0xbfb8aa3b, v66
	v_mul_f32_e32 v67, 0xbfb8aa3b, v67
	ds_bpermute_b32 v142, v134, v2
	ds_bpermute_b32 v143, v134, v3
	ds_bpermute_b32 v144, v134, v4
	ds_bpermute_b32 v145, v134, v5
	v_mov_b64_e32 v[148:149], v[8:9]
	s_waitcnt lgkmcnt(4)
	global_store_dwordx4 v[146:147], v[138:141], off
	v_or_b32_e32 v8, 2, v135
	v_exp_f32_e32 v78, v78
	v_exp_f32_e32 v79, v79
	v_exp_f32_e32 v66, v66
	v_exp_f32_e32 v67, v67
	v_mad_i64_i32 v[8:9], s[4:5], v8, s92, v[6:7]
	v_add_f32_e32 v70, 1.0, v70
	v_add_f32_e32 v71, 1.0, v71
	v_cvt_pk_bf16_f32 v2, v26, v27
	v_cvt_pk_bf16_f32 v3, v28, v29
	v_cvt_pk_bf16_f32 v4, v42, v43
	v_cvt_pk_bf16_f32 v5, v44, v45
	v_lshl_add_u64 v[8:9], v[8:9], 0, v[132:133]
	v_rcp_f32_e32 v70, v70
	v_rcp_f32_e32 v71, v71
	v_pk_mul_f32 v[68:69], v[68:69], v[74:75]
	v_mul_f32_e32 v74, 0xbfb8aa3b, v64
	v_mul_f32_e32 v75, 0xbfb8aa3b, v65
	ds_bpermute_b32 v138, v134, v2
	ds_bpermute_b32 v139, v134, v3
	ds_bpermute_b32 v140, v134, v4
	ds_bpermute_b32 v141, v134, v5
	v_mov_b64_e32 v[146:147], v[8:9]
	s_waitcnt lgkmcnt(4)
	global_store_dwordx4 v[148:149], v[142:145], off
	v_or_b32_e32 v8, 3, v135
	v_exp_f32_e32 v74, v74
	v_exp_f32_e32 v75, v75
	v_mad_i64_i32 v[8:9], s[4:5], v8, s92, v[6:7]
	v_add_f32_e32 v78, 1.0, v78
	v_add_f32_e32 v79, 1.0, v79
	v_add_f32_e32 v66, 1.0, v66
	v_add_f32_e32 v67, 1.0, v67
	v_cvt_pk_bf16_f32 v2, v30, v31
	v_cvt_pk_bf16_f32 v3, v32, v33
	v_cvt_pk_bf16_f32 v4, v46, v47
	v_cvt_pk_bf16_f32 v5, v48, v49
	v_lshl_add_u64 v[8:9], v[8:9], 0, v[132:133]
	v_rcp_f32_e32 v78, v78
	v_rcp_f32_e32 v79, v79
	v_rcp_f32_e32 v66, v66
	v_rcp_f32_e32 v67, v67
	ds_bpermute_b32 v142, v134, v2
	ds_bpermute_b32 v143, v134, v3
	ds_bpermute_b32 v144, v134, v4
	ds_bpermute_b32 v145, v134, v5
	v_mov_b64_e32 v[148:149], v[8:9]
	s_waitcnt lgkmcnt(4)
	global_store_dwordx4 v[146:147], v[138:141], off
	v_or_b32_e32 v8, 4, v135
	v_pk_mul_f32 v[70:71], v[70:71], v[80:81]
	v_mad_i64_i32 v[8:9], s[4:5], v8, s92, v[6:7]
	v_add_f32_e32 v74, 1.0, v74
	v_add_f32_e32 v75, 1.0, v75
	v_cvt_pk_bf16_f32 v2, v34, v35
	v_cvt_pk_bf16_f32 v3, v36, v37
	v_cvt_pk_bf16_f32 v4, v72, v73
	v_cvt_pk_bf16_f32 v5, v70, v71
	v_lshl_add_u64 v[8:9], v[8:9], 0, v[132:133]
	v_rcp_f32_e32 v74, v74
	v_rcp_f32_e32 v75, v75
	ds_bpermute_b32 v138, v134, v2
	ds_bpermute_b32 v139, v134, v3
	ds_bpermute_b32 v140, v134, v4
	ds_bpermute_b32 v141, v134, v5
	v_mov_b64_e32 v[146:147], v[8:9]
	s_waitcnt lgkmcnt(4)
	global_store_dwordx4 v[148:149], v[142:145], off
	v_or_b32_e32 v8, 5, v135
	v_pk_mul_f32 v[68:69], v[78:79], v[68:69]
	v_pk_mul_f32 v[66:67], v[66:67], v[76:77]
	v_mad_i64_i32 v[8:9], s[4:5], v8, s92, v[6:7]
	v_cvt_pk_bf16_f32 v2, v38, v39
	v_cvt_pk_bf16_f32 v3, v40, v41
	v_cvt_pk_bf16_f32 v4, v68, v69
	v_cvt_pk_bf16_f32 v5, v66, v67
	v_lshl_add_u64 v[8:9], v[8:9], 0, v[132:133]
	v_pk_mul_f32 v[10:11], v[64:65], v[10:11]
	ds_bpermute_b32 v142, v134, v2
	ds_bpermute_b32 v143, v134, v3
	ds_bpermute_b32 v144, v134, v4
	ds_bpermute_b32 v145, v134, v5
	v_mov_b64_e32 v[148:149], v[8:9]
	s_waitcnt lgkmcnt(4)
	global_store_dwordx4 v[146:147], v[138:141], off
	v_or_b32_e32 v8, 6, v135
	v_pk_mul_f32 v[10:11], v[74:75], v[10:11]
	v_mad_i64_i32 v[8:9], s[4:5], v8, s92, v[6:7]
	v_cvt_pk_bf16_f32 v2, v50, v51
	v_cvt_pk_bf16_f32 v3, v52, v53
	v_cvt_pk_bf16_f32 v4, v10, v11
	v_cvt_pk_bf16_f32 v5, v14, v15
	v_lshl_add_u64 v[8:9], v[8:9], 0, v[132:133]
	ds_bpermute_b32 v138, v134, v2
	ds_bpermute_b32 v139, v134, v3
	ds_bpermute_b32 v140, v134, v4
	ds_bpermute_b32 v141, v134, v5
	v_mov_b64_e32 v[146:147], v[8:9]
	s_waitcnt lgkmcnt(4)
	global_store_dwordx4 v[148:149], v[142:145], off
	v_or_b32_e32 v8, 7, v135
	v_mad_i64_i32 v[6:7], s[4:5], v8, s92, v[6:7]
	v_cvt_pk_bf16_f32 v2, v54, v55
	v_cvt_pk_bf16_f32 v3, v56, v57
	v_cvt_pk_bf16_f32 v4, v60, v61
	v_cvt_pk_bf16_f32 v5, v58, v59
	v_lshl_add_u64 v[6:7], v[6:7], 0, v[132:133]
	ds_bpermute_b32 v142, v134, v2
	ds_bpermute_b32 v143, v134, v3
	ds_bpermute_b32 v144, v134, v4
	ds_bpermute_b32 v145, v134, v5
	v_mov_b64_e32 v[148:149], v[6:7]
	s_waitcnt lgkmcnt(4)
	global_store_dwordx4 v[146:147], v[138:141], off
	s_andn2_b64 vcc, exec, s[40:41]
	s_waitcnt lgkmcnt(0)
	global_store_dwordx4 v[148:149], v[142:145], off
	s_cbranch_vccnz .LBB0_386
	s_andn2_b64 vcc, exec, s[24:25]
	s_cbranch_vccnz .LBB0_385
	s_barrier
	s_branch .LBB0_385
